# residual epilogues of out-proj and ffn-down GEMMs: two row groups of base loads in flight, in-place FMAs, stores never waited
# speedup vs baseline: 1.0061x; 1.0005x over previous
; #define EPI_FENCE() asm volatile("" ::: "memory")
;     __device__ __forceinline__ void operator()(const Acc& acc, const Unit& u, int wr, int wc, int fr, int fq) const {
;         const int row0 = u.pm * BM + wr * 64 + fr, col0 = u.pn * BM + wc * 32 + 8 * fq;
;         const float* gp = gate + (size_t)(u.pm >> 4) * ADAW + col0;
;         f32x4 gv[2][2];
; #pragma unroll
;         for (int bj = 0; bj < 2; ++bj) { gv[bj][0] = *(const f32x4*)(gp + bj * HALF); gv[bj][1] = *(const f32x4*)(gp + bj * HALF + 4); }
; #pragma unroll
;         for (int ai = 0; ai < 2; ++ai)
; #pragma unroll
;             for (int m = 0; m < 4; ++m) { const size_t off = (size_t)(row0 + ai * HALF + m * 16) * DM + col0;
; #pragma unroll
;                 for (int bj = 0; bj < 2; ++bj) {
;                     const f32x4 b0 = *(const f32x4*)(base + off + bj * HALF), b1 = *(const f32x4*)(base + off + bj * HALF + 4);
;                     *(f32x4*)(out + off + bj * HALF) = b0 + gv[bj][0] * acc[ai][bj][m][0];
;                     *(f32x4*)(out + off + bj * HALF + 4) = b1 + gv[bj][1] * acc[ai][bj][m][1]; }
;                 EPI_FENCE(); }
;     }
.LBB0_825:
	v_lshl_add_u32 v184, s44, 8, v168
	v_lshl_or_b32 v182, s60, 8, v170
	s_ashr_i32 s0, s44, 4
	v_ashrrev_i32_e32 v185, 31, v184
	s_mul_hi_i32 s1, s0, 0xc000
	s_mul_i32 s0, s0, 0xc000
	v_ashrrev_i32_e32 v183, 31, v182
	v_lshlrev_b64 v[128:129], 11, v[184:185]
	s_add_u32 s0, s53, s0
	v_lshl_add_u64 v[128:129], v[128:129], 0, v[182:183]
	s_addc_u32 s1, s54, s1
	v_lshlrev_b64 v[160:161], 2, v[128:129]
	v_lshl_add_u64 v[132:133], v[182:183], 2, s[0:1]
	v_lshl_add_u64 v[186:187], s[36:37], 0, v[160:161]
	v_lshl_add_u64 v[188:189], s[68:69], 0, v[160:161]
	s_andn2_b64 vcc, exec, s[2:3]
	s_mov_b64 s[0:1], -1
	global_load_dwordx4 v[140:143], v[132:133], off
	global_load_dwordx4 v[136:139], v[132:133], off offset:16
	global_load_dwordx4 v[128:131], v[132:133], off offset:528
	global_load_dwordx4 v[132:135], v[132:133], off offset:512
	s_mov_b32 s99, 0
	global_load_dwordx4 v[190:193], v[186:187], off
	global_load_dwordx4 v[194:197], v[186:187], off offset:16
	global_load_dwordx4 v[198:201], v[186:187], off offset:512
	global_load_dwordx4 v[202:205], v[186:187], off offset:528
	s_mov_b32 s98, 0x20000
	v_lshl_add_u64 v[186:187], v[186:187], 0, s[98:99]
	global_load_dwordx4 v[206:209], v[186:187], off
	global_load_dwordx4 v[210:213], v[186:187], off offset:16
	global_load_dwordx4 v[214:217], v[186:187], off offset:512
	global_load_dwordx4 v[220:223], v[186:187], off offset:528
	s_mov_b32 s98, 0x20000
	v_lshl_add_u64 v[186:187], v[186:187], 0, s[98:99]
	s_waitcnt vmcnt(4)
	v_pk_fma_f32 v[126:127], v[126:127], v[142:143], v[192:193]
	v_pk_fma_f32 v[124:125], v[124:125], v[140:141], v[190:191]
	v_pk_fma_f32 v[122:123], v[122:123], v[138:139], v[196:197]
	v_pk_fma_f32 v[120:121], v[120:121], v[136:137], v[194:195]
	v_pk_fma_f32 v[114:115], v[114:115], v[134:135], v[200:201]
	v_pk_fma_f32 v[112:113], v[112:113], v[132:133], v[198:199]
	v_pk_fma_f32 v[110:111], v[110:111], v[130:131], v[204:205]
	v_pk_fma_f32 v[108:109], v[108:109], v[128:129], v[202:203]
	global_store_dwordx4 v[188:189], v[124:127], off
	global_store_dwordx4 v[188:189], v[120:123], off offset:16
	global_store_dwordx4 v[188:189], v[112:115], off offset:512
	global_store_dwordx4 v[188:189], v[108:111], off offset:528
	s_mov_b32 s98, 0x20000
	v_lshl_add_u64 v[188:189], v[188:189], 0, s[98:99]
	global_load_dwordx4 v[190:193], v[186:187], off
	global_load_dwordx4 v[194:197], v[186:187], off offset:16
	global_load_dwordx4 v[198:201], v[186:187], off offset:512
	global_load_dwordx4 v[202:205], v[186:187], off offset:528
	s_mov_b32 s98, 0x20000
	v_lshl_add_u64 v[186:187], v[186:187], 0, s[98:99]
	s_waitcnt vmcnt(8)
	v_pk_fma_f32 v[118:119], v[118:119], v[142:143], v[208:209]
	v_pk_fma_f32 v[116:117], v[116:117], v[140:141], v[206:207]
	v_pk_fma_f32 v[106:107], v[106:107], v[138:139], v[212:213]
	v_pk_fma_f32 v[104:105], v[104:105], v[136:137], v[210:211]
	v_pk_fma_f32 v[98:99], v[98:99], v[134:135], v[216:217]
	v_pk_fma_f32 v[96:97], v[96:97], v[132:133], v[214:215]
	v_pk_fma_f32 v[94:95], v[94:95], v[130:131], v[222:223]
	v_pk_fma_f32 v[92:93], v[92:93], v[128:129], v[220:221]
	global_store_dwordx4 v[188:189], v[116:119], off
	global_store_dwordx4 v[188:189], v[104:107], off offset:16
	global_store_dwordx4 v[188:189], v[96:99], off offset:512
	global_store_dwordx4 v[188:189], v[92:95], off offset:528
	s_mov_b32 s98, 0x20000
	v_lshl_add_u64 v[188:189], v[188:189], 0, s[98:99]
	global_load_dwordx4 v[206:209], v[186:187], off
	global_load_dwordx4 v[210:213], v[186:187], off offset:16
	global_load_dwordx4 v[214:217], v[186:187], off offset:512
	global_load_dwordx4 v[220:223], v[186:187], off offset:528
	s_mov_b32 s98, 0xa0000
	v_lshl_add_u64 v[186:187], v[186:187], 0, s[98:99]
	s_waitcnt vmcnt(8)
	v_pk_fma_f32 v[102:103], v[102:103], v[142:143], v[192:193]
	v_pk_fma_f32 v[100:101], v[100:101], v[140:141], v[190:191]
	v_pk_fma_f32 v[90:91], v[90:91], v[138:139], v[196:197]
	v_pk_fma_f32 v[88:89], v[88:89], v[136:137], v[194:195]
	v_pk_fma_f32 v[82:83], v[82:83], v[134:135], v[200:201]
	v_pk_fma_f32 v[80:81], v[80:81], v[132:133], v[198:199]
	v_pk_fma_f32 v[78:79], v[78:79], v[130:131], v[204:205]
	v_pk_fma_f32 v[76:77], v[76:77], v[128:129], v[202:203]
	global_store_dwordx4 v[188:189], v[100:103], off
	global_store_dwordx4 v[188:189], v[88:91], off offset:16
	global_store_dwordx4 v[188:189], v[80:83], off offset:512
	global_store_dwordx4 v[188:189], v[76:79], off offset:528
	s_mov_b32 s98, 0x20000
	v_lshl_add_u64 v[188:189], v[188:189], 0, s[98:99]
	global_load_dwordx4 v[190:193], v[186:187], off
	global_load_dwordx4 v[194:197], v[186:187], off offset:16
	global_load_dwordx4 v[198:201], v[186:187], off offset:512
	global_load_dwordx4 v[202:205], v[186:187], off offset:528
	s_mov_b32 s98, 0x20000
	v_lshl_add_u64 v[186:187], v[186:187], 0, s[98:99]
	s_waitcnt vmcnt(8)
; #define EPI_FENCE() asm volatile("" ::: "memory")
;     __device__ __forceinline__ void operator()(const Acc& acc, const Unit& u, int wr, int wc, int fr, int fq) const {
;         const int row0 = u.pm * BM + wr * 64 + fr, col0 = u.pn * BM + wc * 32 + 8 * fq;
;         const float* gp = gate + (size_t)(u.pm >> 4) * ADAW + col0;
;         f32x4 gv[2][2];
; #pragma unroll
;         for (int bj = 0; bj < 2; ++bj) { gv[bj][0] = *(const f32x4*)(gp + bj * HALF); gv[bj][1] = *(const f32x4*)(gp + bj * HALF + 4); }
; #pragma unroll
;         for (int ai = 0; ai < 2; ++ai)
; #pragma unroll
;             for (int m = 0; m < 4; ++m) { const size_t off = (size_t)(row0 + ai * HALF + m * 16) * DM + col0;
; #pragma unroll
;                 for (int bj = 0; bj < 2; ++bj) {
;                     const f32x4 b0 = *(const f32x4*)(base + off + bj * HALF), b1 = *(const f32x4*)(base + off + bj * HALF + 4);
;                     *(f32x4*)(out + off + bj * HALF) = b0 + gv[bj][0] * acc[ai][bj][m][0];
;                     *(f32x4*)(out + off + bj * HALF + 4) = b1 + gv[bj][1] * acc[ai][bj][m][1]; }
;                 EPI_FENCE(); }
;     }
	v_pk_fma_f32 v[86:87], v[86:87], v[142:143], v[208:209]
	v_pk_fma_f32 v[84:85], v[84:85], v[140:141], v[206:207]
	v_pk_fma_f32 v[74:75], v[74:75], v[138:139], v[212:213]
	v_pk_fma_f32 v[72:73], v[72:73], v[136:137], v[210:211]
	v_pk_fma_f32 v[70:71], v[70:71], v[134:135], v[216:217]
	v_pk_fma_f32 v[68:69], v[68:69], v[132:133], v[214:215]
	v_pk_fma_f32 v[66:67], v[66:67], v[130:131], v[222:223]
	v_pk_fma_f32 v[64:65], v[64:65], v[128:129], v[220:221]
	global_store_dwordx4 v[188:189], v[84:87], off
	global_store_dwordx4 v[188:189], v[72:75], off offset:16
	global_store_dwordx4 v[188:189], v[68:71], off offset:512
	global_store_dwordx4 v[188:189], v[64:67], off offset:528
	s_mov_b32 s98, 0xa0000
	v_lshl_add_u64 v[188:189], v[188:189], 0, s[98:99]
	global_load_dwordx4 v[206:209], v[186:187], off
	global_load_dwordx4 v[210:213], v[186:187], off offset:16
	global_load_dwordx4 v[214:217], v[186:187], off offset:512
	global_load_dwordx4 v[220:223], v[186:187], off offset:528
	s_mov_b32 s98, 0x20000
	v_lshl_add_u64 v[186:187], v[186:187], 0, s[98:99]
	s_waitcnt vmcnt(8)
	v_pk_fma_f32 v[62:63], v[62:63], v[142:143], v[192:193]
	v_pk_fma_f32 v[60:61], v[60:61], v[140:141], v[190:191]
	v_pk_fma_f32 v[58:59], v[58:59], v[138:139], v[196:197]
	v_pk_fma_f32 v[56:57], v[56:57], v[136:137], v[194:195]
	v_pk_fma_f32 v[50:51], v[50:51], v[134:135], v[200:201]
	v_pk_fma_f32 v[48:49], v[48:49], v[132:133], v[198:199]
	v_pk_fma_f32 v[46:47], v[46:47], v[130:131], v[204:205]
	v_pk_fma_f32 v[44:45], v[44:45], v[128:129], v[202:203]
	global_store_dwordx4 v[188:189], v[60:63], off
	global_store_dwordx4 v[188:189], v[56:59], off offset:16
	global_store_dwordx4 v[188:189], v[48:51], off offset:512
	global_store_dwordx4 v[188:189], v[44:47], off offset:528
	s_mov_b32 s98, 0x20000
	v_lshl_add_u64 v[188:189], v[188:189], 0, s[98:99]
	global_load_dwordx4 v[190:193], v[186:187], off
	global_load_dwordx4 v[194:197], v[186:187], off offset:16
	global_load_dwordx4 v[198:201], v[186:187], off offset:512
	global_load_dwordx4 v[202:205], v[186:187], off offset:528
	s_mov_b32 s98, 0x20000
	v_lshl_add_u64 v[186:187], v[186:187], 0, s[98:99]
	s_waitcnt vmcnt(8)
	v_pk_fma_f32 v[54:55], v[54:55], v[142:143], v[208:209]
	v_pk_fma_f32 v[52:53], v[52:53], v[140:141], v[206:207]
	v_pk_fma_f32 v[42:43], v[42:43], v[138:139], v[212:213]
	v_pk_fma_f32 v[40:41], v[40:41], v[136:137], v[210:211]
	v_pk_fma_f32 v[34:35], v[34:35], v[134:135], v[216:217]
	v_pk_fma_f32 v[32:33], v[32:33], v[132:133], v[214:215]
	v_pk_fma_f32 v[30:31], v[30:31], v[130:131], v[222:223]
	v_pk_fma_f32 v[28:29], v[28:29], v[128:129], v[220:221]
	global_store_dwordx4 v[188:189], v[52:55], off
	global_store_dwordx4 v[188:189], v[40:43], off offset:16
	global_store_dwordx4 v[188:189], v[32:35], off offset:512
	global_store_dwordx4 v[188:189], v[28:31], off offset:528
	s_mov_b32 s98, 0x20000
	v_lshl_add_u64 v[188:189], v[188:189], 0, s[98:99]
	global_load_dwordx4 v[206:209], v[186:187], off
	global_load_dwordx4 v[210:213], v[186:187], off offset:16
	global_load_dwordx4 v[214:217], v[186:187], off offset:512
	global_load_dwordx4 v[220:223], v[186:187], off offset:528
	s_waitcnt vmcnt(8)
	v_pk_fma_f32 v[38:39], v[38:39], v[142:143], v[192:193]
	v_pk_fma_f32 v[36:37], v[36:37], v[140:141], v[190:191]
	v_pk_fma_f32 v[26:27], v[26:27], v[138:139], v[196:197]
	v_pk_fma_f32 v[24:25], v[24:25], v[136:137], v[194:195]
	v_pk_fma_f32 v[18:19], v[18:19], v[134:135], v[200:201]
	v_pk_fma_f32 v[16:17], v[16:17], v[132:133], v[198:199]
	v_pk_fma_f32 v[14:15], v[14:15], v[130:131], v[204:205]
	v_pk_fma_f32 v[12:13], v[12:13], v[128:129], v[202:203]
	global_store_dwordx4 v[188:189], v[36:39], off
	global_store_dwordx4 v[188:189], v[24:27], off offset:16
	global_store_dwordx4 v[188:189], v[16:19], off offset:512
	global_store_dwordx4 v[188:189], v[12:15], off offset:528
	s_mov_b32 s98, 0x20000
	v_lshl_add_u64 v[188:189], v[188:189], 0, s[98:99]
	s_waitcnt vmcnt(4)
	v_pk_fma_f32 v[22:23], v[22:23], v[142:143], v[208:209]
	v_pk_fma_f32 v[20:21], v[20:21], v[140:141], v[206:207]
	v_pk_fma_f32 v[10:11], v[10:11], v[138:139], v[212:213]
	v_pk_fma_f32 v[8:9], v[8:9], v[136:137], v[210:211]
	v_pk_fma_f32 v[6:7], v[6:7], v[134:135], v[216:217]
	v_pk_fma_f32 v[4:5], v[4:5], v[132:133], v[214:215]
	v_pk_fma_f32 v[2:3], v[2:3], v[130:131], v[222:223]
	v_pk_fma_f32 v[0:1], v[0:1], v[128:129], v[220:221]
	global_store_dwordx4 v[188:189], v[20:23], off
	global_store_dwordx4 v[188:189], v[8:11], off offset:16
	global_store_dwordx4 v[188:189], v[4:7], off offset:512
	global_store_dwordx4 v[188:189], v[0:3], off offset:528
	s_cbranch_vccnz .LBB0_814
	s_andn2_b64 vcc, exec, s[6:7]
	s_cbranch_vccnz .LBB0_813
	s_barrier
	s_branch .LBB0_813

; #define EPI_FENCE() asm volatile("" ::: "memory")
;     __device__ __forceinline__ void operator()(const Acc& acc, const Unit& u, int wr, int wc, int fr, int fq) const {
;         const int row0 = u.pm * BM + wr * 64 + fr, col0 = u.pn * BM + wc * 32 + 8 * fq;
;         const float* gp = gate + (size_t)(u.pm >> 4) * ADAW + col0;
;         f32x4 gv[2][2];
; #pragma unroll
;         for (int bj = 0; bj < 2; ++bj) { gv[bj][0] = *(const f32x4*)(gp + bj * HALF); gv[bj][1] = *(const f32x4*)(gp + bj * HALF + 4); }
; #pragma unroll
;         for (int ai = 0; ai < 2; ++ai)
; #pragma unroll
;             for (int m = 0; m < 4; ++m) { const size_t off = (size_t)(row0 + ai * HALF + m * 16) * DM + col0;
; #pragma unroll
;                 for (int bj = 0; bj < 2; ++bj) {
;                     const f32x4 b0 = *(const f32x4*)(base + off + bj * HALF), b1 = *(const f32x4*)(base + off + bj * HALF + 4);
;                     *(f32x4*)(out + off + bj * HALF) = b0 + gv[bj][0] * acc[ai][bj][m][0];
;                     *(f32x4*)(out + off + bj * HALF + 4) = b1 + gv[bj][1] * acc[ai][bj][m][1]; }
;                 EPI_FENCE(); }
;     }
.LBB0_1051:
	v_lshl_or_b32 v128, s52, 8, v164
	s_ashr_i32 s24, s51, 4
	v_lshl_add_u32 v186, s51, 8, v162
	s_mul_hi_i32 s25, s24, 0xc000
	s_mul_i32 s24, s24, 0xc000
	v_ashrrev_i32_e32 v129, 31, v128
	v_ashrrev_i32_e32 v187, 31, v186
	s_add_u32 s24, s38, s24
	v_lshlrev_b64 v[184:185], 2, v[128:129]
	v_lshlrev_b64 v[128:129], 13, v[186:187]
	s_addc_u32 s25, s39, s25
	v_lshl_add_u64 v[128:129], s[68:69], 0, v[128:129]
	v_lshl_add_u64 v[136:137], s[24:25], 0, v[184:185]
	v_lshl_add_u64 v[160:161], v[128:129], 0, v[184:185]
	global_load_dwordx4 v[132:135], v[136:137], off
	global_load_dwordx4 v[128:131], v[136:137], off offset:16
	global_load_dwordx4 v[140:143], v[136:137], off offset:512
	global_load_dwordx4 v[136:139], v[136:137], off offset:528
	v_mov_b32_e32 v188, v160
	v_mov_b32_e32 v189, v161
	s_mov_b32 s99, 0
	global_load_dwordx4 v[168:171], v[160:161], off
	global_load_dwordx4 v[172:175], v[160:161], off offset:16
	global_load_dwordx4 v[176:179], v[160:161], off offset:512
	global_load_dwordx4 v[180:183], v[160:161], off offset:528
	s_mov_b32 s98, 0x20000
	v_lshl_add_u64 v[160:161], v[160:161], 0, s[98:99]
	global_load_dwordx4 v[192:195], v[160:161], off
	global_load_dwordx4 v[196:199], v[160:161], off offset:16
	global_load_dwordx4 v[200:203], v[160:161], off offset:512
	global_load_dwordx4 v[204:207], v[160:161], off offset:528
	s_mov_b32 s98, 0x20000
	v_lshl_add_u64 v[160:161], v[160:161], 0, s[98:99]
	s_waitcnt vmcnt(4)
	v_pk_fma_f32 v[126:127], v[126:127], v[134:135], v[170:171]
	v_pk_fma_f32 v[124:125], v[124:125], v[132:133], v[168:169]
	v_pk_fma_f32 v[122:123], v[122:123], v[130:131], v[174:175]
	v_pk_fma_f32 v[120:121], v[120:121], v[128:129], v[172:173]
	v_pk_fma_f32 v[118:119], v[118:119], v[142:143], v[178:179]
	v_pk_fma_f32 v[116:117], v[116:117], v[140:141], v[176:177]
	v_pk_fma_f32 v[114:115], v[114:115], v[138:139], v[182:183]
	v_pk_fma_f32 v[112:113], v[112:113], v[136:137], v[180:181]
	global_store_dwordx4 v[188:189], v[124:127], off
	global_store_dwordx4 v[188:189], v[120:123], off offset:16
	global_store_dwordx4 v[188:189], v[116:119], off offset:512
	global_store_dwordx4 v[188:189], v[112:115], off offset:528
	s_mov_b32 s98, 0x20000
	v_lshl_add_u64 v[188:189], v[188:189], 0, s[98:99]
	global_load_dwordx4 v[168:171], v[160:161], off
	global_load_dwordx4 v[172:175], v[160:161], off offset:16
	global_load_dwordx4 v[176:179], v[160:161], off offset:512
	global_load_dwordx4 v[180:183], v[160:161], off offset:528
	s_mov_b32 s98, 0x20000
	v_lshl_add_u64 v[160:161], v[160:161], 0, s[98:99]
	s_waitcnt vmcnt(8)
	v_pk_fma_f32 v[110:111], v[110:111], v[134:135], v[194:195]
	v_pk_fma_f32 v[108:109], v[108:109], v[132:133], v[192:193]
	v_pk_fma_f32 v[106:107], v[106:107], v[130:131], v[198:199]
	v_pk_fma_f32 v[104:105], v[104:105], v[128:129], v[196:197]
	v_pk_fma_f32 v[102:103], v[102:103], v[142:143], v[202:203]
	v_pk_fma_f32 v[100:101], v[100:101], v[140:141], v[200:201]
	v_pk_fma_f32 v[98:99], v[98:99], v[138:139], v[206:207]
	v_pk_fma_f32 v[96:97], v[96:97], v[136:137], v[204:205]
	global_store_dwordx4 v[188:189], v[108:111], off
	global_store_dwordx4 v[188:189], v[104:107], off offset:16
	global_store_dwordx4 v[188:189], v[100:103], off offset:512
	global_store_dwordx4 v[188:189], v[96:99], off offset:528
	s_mov_b32 s98, 0x20000
	v_lshl_add_u64 v[188:189], v[188:189], 0, s[98:99]
	global_load_dwordx4 v[192:195], v[160:161], off
	global_load_dwordx4 v[196:199], v[160:161], off offset:16
	global_load_dwordx4 v[200:203], v[160:161], off offset:512
	global_load_dwordx4 v[204:207], v[160:161], off offset:528
	s_mov_b32 s98, 0xa0000
	v_lshl_add_u64 v[160:161], v[160:161], 0, s[98:99]
	s_waitcnt vmcnt(8)
	v_pk_fma_f32 v[94:95], v[94:95], v[134:135], v[170:171]
	v_pk_fma_f32 v[92:93], v[92:93], v[132:133], v[168:169]
	v_pk_fma_f32 v[90:91], v[90:91], v[130:131], v[174:175]
	v_pk_fma_f32 v[88:89], v[88:89], v[128:129], v[172:173]
	v_pk_fma_f32 v[86:87], v[86:87], v[142:143], v[178:179]
	v_pk_fma_f32 v[84:85], v[84:85], v[140:141], v[176:177]
	v_pk_fma_f32 v[82:83], v[82:83], v[138:139], v[182:183]
	v_pk_fma_f32 v[80:81], v[80:81], v[136:137], v[180:181]
	global_store_dwordx4 v[188:189], v[92:95], off
	global_store_dwordx4 v[188:189], v[88:91], off offset:16
	global_store_dwordx4 v[188:189], v[84:87], off offset:512
	global_store_dwordx4 v[188:189], v[80:83], off offset:528
	s_mov_b32 s98, 0x20000
	v_lshl_add_u64 v[188:189], v[188:189], 0, s[98:99]
	global_load_dwordx4 v[168:171], v[160:161], off
	global_load_dwordx4 v[172:175], v[160:161], off offset:16
	global_load_dwordx4 v[176:179], v[160:161], off offset:512
	global_load_dwordx4 v[180:183], v[160:161], off offset:528
	s_mov_b32 s98, 0x20000
	v_lshl_add_u64 v[160:161], v[160:161], 0, s[98:99]
	s_waitcnt vmcnt(8)
; #define EPI_FENCE() asm volatile("" ::: "memory")
;     __device__ __forceinline__ void operator()(const Acc& acc, const Unit& u, int wr, int wc, int fr, int fq) const {
;         const int row0 = u.pm * BM + wr * 64 + fr, col0 = u.pn * BM + wc * 32 + 8 * fq;
;         const float* gp = gate + (size_t)(u.pm >> 4) * ADAW + col0;
;         f32x4 gv[2][2];
; #pragma unroll
;         for (int bj = 0; bj < 2; ++bj) { gv[bj][0] = *(const f32x4*)(gp + bj * HALF); gv[bj][1] = *(const f32x4*)(gp + bj * HALF + 4); }
; #pragma unroll
;         for (int ai = 0; ai < 2; ++ai)
; #pragma unroll
;             for (int m = 0; m < 4; ++m) { const size_t off = (size_t)(row0 + ai * HALF + m * 16) * DM + col0;
; #pragma unroll
;                 for (int bj = 0; bj < 2; ++bj) {
;                     const f32x4 b0 = *(const f32x4*)(base + off + bj * HALF), b1 = *(const f32x4*)(base + off + bj * HALF + 4);
;                     *(f32x4*)(out + off + bj * HALF) = b0 + gv[bj][0] * acc[ai][bj][m][0];
;                     *(f32x4*)(out + off + bj * HALF + 4) = b1 + gv[bj][1] * acc[ai][bj][m][1]; }
;                 EPI_FENCE(); }
;     }
	v_pk_fma_f32 v[78:79], v[78:79], v[134:135], v[194:195]
	v_pk_fma_f32 v[76:77], v[76:77], v[132:133], v[192:193]
	v_pk_fma_f32 v[74:75], v[74:75], v[130:131], v[198:199]
	v_pk_fma_f32 v[72:73], v[72:73], v[128:129], v[196:197]
	v_pk_fma_f32 v[70:71], v[70:71], v[142:143], v[202:203]
	v_pk_fma_f32 v[68:69], v[68:69], v[140:141], v[200:201]
	v_pk_fma_f32 v[66:67], v[66:67], v[138:139], v[206:207]
	v_pk_fma_f32 v[64:65], v[64:65], v[136:137], v[204:205]
	global_store_dwordx4 v[188:189], v[76:79], off
	global_store_dwordx4 v[188:189], v[72:75], off offset:16
	global_store_dwordx4 v[188:189], v[68:71], off offset:512
	global_store_dwordx4 v[188:189], v[64:67], off offset:528
	s_mov_b32 s98, 0xa0000
	v_lshl_add_u64 v[188:189], v[188:189], 0, s[98:99]
	global_load_dwordx4 v[192:195], v[160:161], off
	global_load_dwordx4 v[196:199], v[160:161], off offset:16
	global_load_dwordx4 v[200:203], v[160:161], off offset:512
	global_load_dwordx4 v[204:207], v[160:161], off offset:528
	s_mov_b32 s98, 0x20000
	v_lshl_add_u64 v[160:161], v[160:161], 0, s[98:99]
	s_waitcnt vmcnt(8)
	v_pk_fma_f32 v[62:63], v[62:63], v[134:135], v[170:171]
	v_pk_fma_f32 v[60:61], v[60:61], v[132:133], v[168:169]
	v_pk_fma_f32 v[58:59], v[58:59], v[130:131], v[174:175]
	v_pk_fma_f32 v[56:57], v[56:57], v[128:129], v[172:173]
	v_pk_fma_f32 v[54:55], v[54:55], v[142:143], v[178:179]
	v_pk_fma_f32 v[52:53], v[52:53], v[140:141], v[176:177]
	v_pk_fma_f32 v[50:51], v[50:51], v[138:139], v[182:183]
	v_pk_fma_f32 v[48:49], v[48:49], v[136:137], v[180:181]
	global_store_dwordx4 v[188:189], v[60:63], off
	global_store_dwordx4 v[188:189], v[56:59], off offset:16
	global_store_dwordx4 v[188:189], v[52:55], off offset:512
	global_store_dwordx4 v[188:189], v[48:51], off offset:528
	s_mov_b32 s98, 0x20000
	v_lshl_add_u64 v[188:189], v[188:189], 0, s[98:99]
	global_load_dwordx4 v[168:171], v[160:161], off
	global_load_dwordx4 v[172:175], v[160:161], off offset:16
	global_load_dwordx4 v[176:179], v[160:161], off offset:512
	global_load_dwordx4 v[180:183], v[160:161], off offset:528
	s_mov_b32 s98, 0x20000
	v_lshl_add_u64 v[160:161], v[160:161], 0, s[98:99]
	s_waitcnt vmcnt(8)
	v_pk_fma_f32 v[46:47], v[46:47], v[134:135], v[194:195]
	v_pk_fma_f32 v[44:45], v[44:45], v[132:133], v[192:193]
	v_pk_fma_f32 v[42:43], v[42:43], v[130:131], v[198:199]
	v_pk_fma_f32 v[40:41], v[40:41], v[128:129], v[196:197]
	v_pk_fma_f32 v[38:39], v[38:39], v[142:143], v[202:203]
	v_pk_fma_f32 v[36:37], v[36:37], v[140:141], v[200:201]
	v_pk_fma_f32 v[34:35], v[34:35], v[138:139], v[206:207]
	v_pk_fma_f32 v[32:33], v[32:33], v[136:137], v[204:205]
	global_store_dwordx4 v[188:189], v[44:47], off
	global_store_dwordx4 v[188:189], v[40:43], off offset:16
	global_store_dwordx4 v[188:189], v[36:39], off offset:512
	global_store_dwordx4 v[188:189], v[32:35], off offset:528
	s_mov_b32 s98, 0x20000
	v_lshl_add_u64 v[188:189], v[188:189], 0, s[98:99]
	global_load_dwordx4 v[192:195], v[160:161], off
	global_load_dwordx4 v[196:199], v[160:161], off offset:16
	global_load_dwordx4 v[200:203], v[160:161], off offset:512
	global_load_dwordx4 v[204:207], v[160:161], off offset:528
	s_waitcnt vmcnt(8)
	v_pk_fma_f32 v[30:31], v[30:31], v[134:135], v[170:171]
	v_pk_fma_f32 v[28:29], v[28:29], v[132:133], v[168:169]
	v_pk_fma_f32 v[26:27], v[26:27], v[130:131], v[174:175]
	v_pk_fma_f32 v[24:25], v[24:25], v[128:129], v[172:173]
	v_pk_fma_f32 v[22:23], v[22:23], v[142:143], v[178:179]
	v_pk_fma_f32 v[20:21], v[20:21], v[140:141], v[176:177]
	v_pk_fma_f32 v[18:19], v[18:19], v[138:139], v[182:183]
	v_pk_fma_f32 v[16:17], v[16:17], v[136:137], v[180:181]
	global_store_dwordx4 v[188:189], v[28:31], off
	global_store_dwordx4 v[188:189], v[24:27], off offset:16
	global_store_dwordx4 v[188:189], v[20:23], off offset:512
	global_store_dwordx4 v[188:189], v[16:19], off offset:528
	s_mov_b32 s98, 0x20000
	v_lshl_add_u64 v[188:189], v[188:189], 0, s[98:99]
	s_waitcnt vmcnt(4)
	v_pk_fma_f32 v[14:15], v[14:15], v[134:135], v[194:195]
	v_pk_fma_f32 v[12:13], v[12:13], v[132:133], v[192:193]
	v_pk_fma_f32 v[10:11], v[10:11], v[130:131], v[198:199]
	v_pk_fma_f32 v[8:9], v[8:9], v[128:129], v[196:197]
	v_pk_fma_f32 v[6:7], v[6:7], v[142:143], v[202:203]
	v_pk_fma_f32 v[4:5], v[4:5], v[140:141], v[200:201]
	v_pk_fma_f32 v[2:3], v[2:3], v[138:139], v[206:207]
	v_pk_fma_f32 v[0:1], v[0:1], v[136:137], v[204:205]
	global_store_dwordx4 v[188:189], v[12:15], off
	global_store_dwordx4 v[188:189], v[8:11], off offset:16
	global_store_dwordx4 v[188:189], v[4:7], off offset:512
	global_store_dwordx4 v[188:189], v[0:3], off offset:528
	s_and_b64 vcc, exec, s[0:1]
	s_mov_b64 s[0:1], -1
	s_cbranch_vccnz .LBB0_1036
	s_andn2_b64 vcc, exec, s[6:7]
	s_cbranch_vccnz .LBB0_1035
	s_barrier
	s_branch .LBB0_1035

; __global__ void __launch_bounds__(NTHREADS, 2) fwd_kernel(Args a) {
;     extern __shared__ __attribute__((aligned(16))) unsigned char lds[];
	.amdhsa_kernel _Z10fwd_kernel4Args
		.amdhsa_group_segment_fixed_size 0
		.amdhsa_private_segment_fixed_size 0
		.amdhsa_kernarg_size 472
		.amdhsa_user_sgpr_count 2
		.amdhsa_user_sgpr_dispatch_ptr 0
		.amdhsa_user_sgpr_queue_ptr 0
		.amdhsa_user_sgpr_kernarg_segment_ptr 1
		.amdhsa_user_sgpr_dispatch_id 0
		.amdhsa_user_sgpr_kernarg_preload_length 0
		.amdhsa_user_sgpr_kernarg_preload_offset 0
		.amdhsa_user_sgpr_private_segment_size 0
		.amdhsa_uses_dynamic_stack 0
		.amdhsa_enable_private_segment 0
		.amdhsa_system_sgpr_workgroup_id_x 1
		.amdhsa_system_sgpr_workgroup_id_y 0
		.amdhsa_system_sgpr_workgroup_id_z 0
		.amdhsa_system_sgpr_workgroup_info 0
		.amdhsa_system_vgpr_workitem_id 2
		.amdhsa_next_free_vgpr 253
		.amdhsa_next_free_sgpr 100
		.amdhsa_accum_offset 256
		.amdhsa_reserve_vcc 1
		.amdhsa_float_round_mode_32 0
		.amdhsa_float_round_mode_16_64 0
		.amdhsa_float_denorm_mode_32 3
		.amdhsa_float_denorm_mode_16_64 3
		.amdhsa_dx10_clamp 1
		.amdhsa_ieee_mode 1
		.amdhsa_fp16_overflow 0
		.amdhsa_tg_split 0
		.amdhsa_exception_fp_ieee_invalid_op 0
		.amdhsa_exception_fp_denorm_src 0
		.amdhsa_exception_fp_ieee_div_zero 0
		.amdhsa_exception_fp_ieee_overflow 0
		.amdhsa_exception_fp_ieee_underflow 0
		.amdhsa_exception_fp_ieee_inexact 0
		.amdhsa_exception_int_div_zero 0
	.end_amdhsa_kernel

; __global__ void __launch_bounds__(NTHREADS, 2) fwd_kernel(Args a) {
;     extern __shared__ __attribute__((aligned(16))) unsigned char lds[];
amdhsa.kernels:
  - .agpr_count:     0
    .args:
      - .offset:         0
        .size:           216
        .value_kind:     by_value
      - .offset:         216
        .size:           4
        .value_kind:     hidden_block_count_x
      - .offset:         220
        .size:           4
        .value_kind:     hidden_block_count_y
      - .offset:         224
        .size:           4
        .value_kind:     hidden_block_count_z
      - .offset:         228
        .size:           2
        .value_kind:     hidden_group_size_x
      - .offset:         230
        .size:           2
        .value_kind:     hidden_group_size_y
      - .offset:         232
        .size:           2
        .value_kind:     hidden_group_size_z
      - .offset:         234
        .size:           2
        .value_kind:     hidden_remainder_x
      - .offset:         236
        .size:           2
        .value_kind:     hidden_remainder_y
      - .offset:         238
        .size:           2
        .value_kind:     hidden_remainder_z
      - .offset:         256
        .size:           8
        .value_kind:     hidden_global_offset_x
      - .offset:         264
        .size:           8
        .value_kind:     hidden_global_offset_y
      - .offset:         272
        .size:           8
        .value_kind:     hidden_global_offset_z
      - .offset:         280
        .size:           2
        .value_kind:     hidden_grid_dims
      - .offset:         304
        .size:           8
        .value_kind:     hidden_multigrid_sync_arg
      - .offset:         336
        .size:           4
        .value_kind:     hidden_dynamic_lds_size
    .group_segment_fixed_size: 0
    .kernarg_segment_align: 8
    .kernarg_segment_size: 472
    .language:       OpenCL C
    .language_version:
      - 2
      - 0
    .max_flat_workgroup_size: 512
    .name:           _Z10fwd_kernel4Args
    .private_segment_fixed_size: 0
    .sgpr_count:     106
    .sgpr_spill_count: 31
    .symbol:         _Z10fwd_kernel4Args.kd
    .uniform_work_group_size: 1
    .uses_dynamic_stack: false
    .vgpr_count:     253
    .vgpr_spill_count: 0
    .wavefront_size: 64
